# DeltaNet conv stage: the two tokens of a step are stored as one dword per lane (adjacent-channel lanes exchange halves by DPP + v_perm; even lane writes token t, odd lane token t+1) - half the store i
# baseline (speedup 1.0000x reference)
; __device__ __forceinline__ float bf2f(unsigned short b) { return __uint_as_float(((unsigned)b) << 16); }
; __device__ __forceinline__ void mixer_pre_item(int item, const float* const* in, int l, unsigned char* ws, LAS unsigned char* lds, int tid, int lane, int wave) {
;     ...
;     for (int task = wave; task < 24; task += 8) {
;         const int g = task >> 1, t0 = (task & 1) * 16, kind = g >> 2, hh = g & 3, cc = g * 64 + lane;
;         const float* cw = in[17] + (size_t)l * 4 * 768;
;         const float w0 = cw[cc], w1 = cw[768 + cc], w2 = cw[1536 + cc], w3 = cw[2304 + cc];
;         bf16_t* dst = (bf16_t*)(ws + WS_R2 + (kind == 0 ? R2_DQ : kind == 1 ? R2_DK : R2_DV)) + (g0 + t0) * 256 + hh * 64 + lane;
;         float xm3 = bf2f(STGD[t0 * 768 + cc]), xm2 = bf2f(STGD[(t0 + 1) * 768 + cc]), xm1 = bf2f(STGD[(t0 + 2) * 768 + cc]);
;         const float qs = (kind == 0) ? 0.125f : 1.0f;
.LBB0_614:
	s_waitcnt vmcnt(8)
	v_mov_b32_e32 v148, v152
	v_mov_b32_e32 v149, v153
	v_mov_b32_e32 v150, v154
	v_mov_b32_e32 v151, v155
	v_mov_b32_e32 v152, v168
	v_mov_b32_e32 v153, v169
	v_mov_b32_e32 v154, v170
	v_mov_b32_e32 v155, v171
	s_add_i32 s38, s31, 8
	s_addk_i32 s33, 0x80
	s_addk_i32 s34, 0x100
	s_cmp_gt_i32 s31, 15
	s_mov_b32 s31, s38
	s_cbranch_scc1 .LBB0_633
.LBB0_615:
	s_bfe_u32 s38, s33, 0x10004
	s_lshl_b32 s43, s34, 1
	s_mul_i32 s39, s38, 0x6000
	s_and_b32 s40, s43, 0xffffff80
	s_add_i32 s44, s39, s40
	s_lshl_b32 s38, s38, 4
	s_add_u32 s38, s35, s38
	s_addc_u32 s39, s42, 0
	s_lshl_b32 s40, s31, 5
	s_andn2_b32 s40, s40, 63
	v_or_b32_e32 v8, s40, v35
	v_ashrrev_i32_e32 v9, 31, v8
	v_lshl_add_u64 v[6:7], v[8:9], 2, s[10:11]
	v_add_co_u32_e32 v10, vcc, s37, v6
	s_lshl_b64 s[40:41], s[38:39], 9
	s_nop 0
	v_addc_co_u32_e32 v11, vcc, 0, v7, vcc
	v_add_co_u32_e32 v12, vcc, s77, v6
	s_lshl_b32 s38, s31, 4
	s_nop 0
	v_addc_co_u32_e32 v13, vcc, 0, v7, vcc
	s_nop 0
	s_and_b32 s45, s43, 0x180
	s_and_b32 s43, s38, 16
	s_ashr_i32 s48, s31, 3
	s_cmp_eq_u32 s48, 1
	s_mov_b32 s38, 0x3200000
	s_cselect_b32 s49, s38, 0x4200000
	s_cmp_lt_u32 s31, 8
	s_cselect_b64 vcc, -1, 0
	s_and_b64 s[38:39], vcc, exec
	s_mulk_i32 s43, 0x600
	s_cselect_b32 s49, 0x2200000, s49
	s_add_i32 s38, s43, 0
	v_lshl_add_u32 v8, v8, 1, s38
	ds_read_u16 v9, v8 offset:17920
	ds_read_u16 v11, v8 offset:19456
	ds_read_u16 v8, v8 offset:20992
	s_cmp_lt_i32 s48, 2
	s_cselect_b64 s[38:39], -1, 0
	s_add_u32 s40, s49, s40
	s_addc_u32 s41, 0, s41
	s_or_b32 s40, s40, s45
	v_cndmask_b32_e32 v0, 1.0, v231, vcc
	v_add_u32_e32 v19, s44, v18
	s_mov_b32 s43, 0
	s_waitcnt lgkmcnt(2)
	v_lshlrev_b32_e32 v10, 16, v9
	s_waitcnt lgkmcnt(1)
	v_lshlrev_b32_e32 v13, 16, v11
	s_waitcnt lgkmcnt(0)
	v_lshlrev_b32_e32 v12, 16, v8
	v_lshl_add_u64 v[8:9], v[2:3], 0, s[40:41]
	v_mov_b32_e32 v5, v148
	v_mov_b32_e32 v4, v149
	v_mov_b32_e32 v6, v150
	v_mov_b32_e32 v7, v151
	v_mov_b32_e32 v116, v10
	v_mov_b32_e32 v117, v13
	v_mov_b32_e32 v118, v13
	v_mov_b32_e32 v119, v12
	v_mov_b32_e32 v134, 0xbfb8aa3b
	v_mov_b32_e32 v136, 1.0
	v_and_b32_e32 v144, 1, v34
	v_cmp_eq_u32_e32 vcc, 1, v144
	v_mov_b32_e32 v132, 0x5040100
	v_mov_b32_e32 v145, 0x3020706
	v_cndmask_b32_e32 v132, v132, v145, vcc
	v_mul_u32_u24_e32 v144, 0x1fe, v144
	v_mov_b32_e32 v145, 0
	v_lshl_add_u64 v[8:9], v[8:9], 0, v[144:145]

; __device__ __forceinline__ float bf2f(unsigned short b) { return __uint_as_float(((unsigned)b) << 16); }
; __device__ __forceinline__ unsigned short f2bf(float f) { return (unsigned short)(pg8::cvt_pk_bf16(f, 0.f) & 0xffffu); }
; __device__ __forceinline__ float siluf_(float x) { return x * __builtin_amdgcn_rcpf(1.0f + __expf(-x)); }
; __device__ __forceinline__ void mixer_pre_item(int item, const float* const* in, int l, unsigned char* ws, LAS unsigned char* lds, int tid, int lane, int wave) {
;     ...
;         for (int t = 0; t < 16; ++t) { const float xc = bf2f(STGD[(t0 + t + 3) * 768 + cc]); float y = siluf_(w0 * xm3 + w1 * xm2 + w2 * xm1 + w3 * xc);
;             if (kind < 2) { const float ss = wave_sum(y * y); y *= qs * __builtin_amdgcn_rsqf(ss + EPS); }
;             dst[(size_t)t * 256] = f2bf(y);
;             xm3 = xm2; xm2 = xm1; xm1 = xc; }
.Lcv_nn0:
	v_cvt_pk_bf16_f32 v126, v128, v129
	s_nop 1
	v_mov_b32_dpp v127, v126 quad_perm:[1,0,3,2] row_mask:0xf bank_mask:0xf bound_ctrl:1
	v_perm_b32 v126, v127, v126, v132
	global_store_dword v[8:9], v126, off offset:-2048
	s_waitcnt lgkmcnt(4)
	v_lshlrev_b32_e32 v117, 16, v110
	v_lshlrev_b32_e32 v118, 16, v110
	v_lshlrev_b32_e32 v119, 16, v111
	v_mov_b32_e32 v116, v123
	v_pk_mul_f32 v[124:125], v[120:121], v[4:5] op_sel:[0,1]
	v_pk_mul_f32 v[126:127], v[122:123], v[4:5] op_sel_hi:[1,0]
	v_pk_mul_f32 v[130:131], v[116:117], v[6:7] op_sel_hi:[1,0]
	v_pk_add_f32 v[128:129], v[124:125], v[126:127]
	v_pk_mul_f32 v[124:125], v[118:119], v[6:7] op_sel:[0,1]
	v_pk_add_f32 v[128:129], v[130:131], v[128:129]
	v_pk_add_f32 v[128:129], v[128:129], v[124:125]
	v_pk_mul_f32 v[130:131], v[128:129], v[134:135] op_sel_hi:[1,0]
	v_exp_f32_e32 v130, v130
	v_exp_f32_e32 v131, v131
	s_nop 0
	v_pk_add_f32 v[130:131], v[130:131], v[136:137] op_sel_hi:[1,0]
	v_rcp_f32_e32 v130, v130
	v_rcp_f32_e32 v131, v131
	s_nop 0
	v_pk_mul_f32 v[128:129], v[128:129], v[130:131]
	s_and_b64 vcc, exec, s[38:39]
	s_cbranch_vccz .Lcv_nn1
	v_mul_f32_e32 v138, v128, v128
	v_mul_f32_e32 v139, v129, v129
	s_nop 0
	v_mov_b32_dpp v138, v138 quad_perm:[1,0,3,2] row_mask:0xf bank_mask:0xf bound_ctrl:1
	v_mov_b32_dpp v139, v139 quad_perm:[1,0,3,2] row_mask:0xf bank_mask:0xf bound_ctrl:1
	v_fmac_f32_e32 v138, v128, v128
	v_fmac_f32_e32 v139, v129, v129
	s_nop 0
	v_add_f32_dpp v138, v138, v138 quad_perm:[2,3,0,1] row_mask:0xf bank_mask:0xf bound_ctrl:1
	v_add_f32_dpp v139, v139, v139 quad_perm:[2,3,0,1] row_mask:0xf bank_mask:0xf bound_ctrl:1
	s_nop 0
	v_add_f32_dpp v138, v138, v138 row_half_mirror row_mask:0xf bank_mask:0xf bound_ctrl:1
	v_add_f32_dpp v139, v139, v139 row_half_mirror row_mask:0xf bank_mask:0xf bound_ctrl:1
	s_nop 0
	v_add_f32_dpp v138, v138, v138 row_mirror row_mask:0xf bank_mask:0xf bound_ctrl:1
	v_add_f32_dpp v139, v139, v139 row_mirror row_mask:0xf bank_mask:0xf bound_ctrl:1
	s_nop 0
	v_readlane_b32 s48, v138, 16
	v_readlane_b32 s49, v138, 48
	v_readlane_b32 s44, v138, 0
	v_readlane_b32 s45, v138, 32
	v_readlane_b32 s100, v139, 16
	v_readlane_b32 s101, v139, 48
	v_readlane_b32 s40, v139, 0
	v_readlane_b32 s41, v139, 32
	v_mov_b32_e32 v140, s48
	v_mov_b32_e32 v141, s49
	v_mov_b32_e32 v142, s100
	v_mov_b32_e32 v143, s101
	v_pk_add_f32 v[140:141], s[44:45], v[140:141]
	v_pk_add_f32 v[142:143], s[40:41], v[142:143]
	v_add_f32_e32 v138, v140, v141
	v_add_f32_e32 v139, v142, v143
	v_add_f32_e32 v138, 0x358637bd, v138
	v_add_f32_e32 v139, 0x358637bd, v139
	v_rsq_f32_e32 v138, v138
	v_rsq_f32_e32 v139, v139
	s_nop 0
	v_mul_f32_e32 v138, v0, v138
	v_mul_f32_e32 v139, v0, v139
	v_mul_f32_e32 v128, v128, v138
	v_mul_f32_e32 v129, v129, v139
.Lcv_nn1:
	v_cvt_pk_bf16_f32 v126, v128, v129
	s_nop 1
	v_mov_b32_dpp v127, v126 quad_perm:[1,0,3,2] row_mask:0xf bank_mask:0xf bound_ctrl:1
	v_perm_b32 v126, v127, v126, v132
	global_store_dword v[8:9], v126, off offset:-1024
	s_waitcnt lgkmcnt(2)
	v_lshlrev_b32_e32 v121, 16, v112
	v_lshlrev_b32_e32 v122, 16, v112
	v_lshlrev_b32_e32 v123, 16, v113
	v_mov_b32_e32 v120, v119
	v_pk_mul_f32 v[124:125], v[116:117], v[4:5] op_sel:[0,1]
	v_pk_mul_f32 v[126:127], v[118:119], v[4:5] op_sel_hi:[1,0]
	v_pk_mul_f32 v[130:131], v[120:121], v[6:7] op_sel_hi:[1,0]
	v_pk_add_f32 v[128:129], v[124:125], v[126:127]
	v_pk_mul_f32 v[124:125], v[122:123], v[6:7] op_sel:[0,1]
	v_pk_add_f32 v[128:129], v[130:131], v[128:129]
	v_pk_add_f32 v[128:129], v[128:129], v[124:125]
	v_pk_mul_f32 v[130:131], v[128:129], v[134:135] op_sel_hi:[1,0]
	v_exp_f32_e32 v130, v130
	v_exp_f32_e32 v131, v131
	s_nop 0
	v_pk_add_f32 v[130:131], v[130:131], v[136:137] op_sel_hi:[1,0]
	v_rcp_f32_e32 v130, v130
	v_rcp_f32_e32 v131, v131
	s_nop 0
	v_pk_mul_f32 v[128:129], v[128:129], v[130:131]
	s_and_b64 vcc, exec, s[38:39]
	s_cbranch_vccz .Lcv_nn2
	v_mul_f32_e32 v138, v128, v128
	v_mul_f32_e32 v139, v129, v129
	s_nop 0
	v_mov_b32_dpp v138, v138 quad_perm:[1,0,3,2] row_mask:0xf bank_mask:0xf bound_ctrl:1
	v_mov_b32_dpp v139, v139 quad_perm:[1,0,3,2] row_mask:0xf bank_mask:0xf bound_ctrl:1
	v_fmac_f32_e32 v138, v128, v128
	v_fmac_f32_e32 v139, v129, v129
	s_nop 0
	v_add_f32_dpp v138, v138, v138 quad_perm:[2,3,0,1] row_mask:0xf bank_mask:0xf bound_ctrl:1
	v_add_f32_dpp v139, v139, v139 quad_perm:[2,3,0,1] row_mask:0xf bank_mask:0xf bound_ctrl:1
	s_nop 0
	v_add_f32_dpp v138, v138, v138 row_half_mirror row_mask:0xf bank_mask:0xf bound_ctrl:1
	v_add_f32_dpp v139, v139, v139 row_half_mirror row_mask:0xf bank_mask:0xf bound_ctrl:1
	s_nop 0
	v_add_f32_dpp v138, v138, v138 row_mirror row_mask:0xf bank_mask:0xf bound_ctrl:1
	v_add_f32_dpp v139, v139, v139 row_mirror row_mask:0xf bank_mask:0xf bound_ctrl:1
	s_nop 0
	v_readlane_b32 s48, v138, 16
	v_readlane_b32 s49, v138, 48
	v_readlane_b32 s44, v138, 0
	v_readlane_b32 s45, v138, 32
	v_readlane_b32 s100, v139, 16
	v_readlane_b32 s101, v139, 48
	v_readlane_b32 s40, v139, 0
	v_readlane_b32 s41, v139, 32
	v_mov_b32_e32 v140, s48
	v_mov_b32_e32 v141, s49
	v_mov_b32_e32 v142, s100
	v_mov_b32_e32 v143, s101
	v_pk_add_f32 v[140:141], s[44:45], v[140:141]
	v_pk_add_f32 v[142:143], s[40:41], v[142:143]
	v_add_f32_e32 v138, v140, v141
	v_add_f32_e32 v139, v142, v143
	v_add_f32_e32 v138, 0x358637bd, v138
	v_add_f32_e32 v139, 0x358637bd, v139
	v_rsq_f32_e32 v138, v138
	v_rsq_f32_e32 v139, v139
	s_nop 0
	v_mul_f32_e32 v138, v0, v138
	v_mul_f32_e32 v139, v0, v139
	v_mul_f32_e32 v128, v128, v138
	v_mul_f32_e32 v129, v129, v139
; __device__ __forceinline__ float bf2f(unsigned short b) { return __uint_as_float(((unsigned)b) << 16); }
; __device__ __forceinline__ unsigned short f2bf(float f) { return (unsigned short)(pg8::cvt_pk_bf16(f, 0.f) & 0xffffu); }
; __device__ __forceinline__ float sigmoidf_(float x) { return __builtin_amdgcn_rcpf(1.0f + __expf(-x)); }
; __device__ __forceinline__ float siluf_(float x) { return x * __builtin_amdgcn_rcpf(1.0f + __expf(-x)); }
; __device__ __forceinline__ float softplusf_(float x) { const float e = __expf(-fabsf(x)); const float lg = (e < 0.03f) ? e * (1.0f - e * (0.5f - e * (0.33333334f - 0.25f * e))) : __logf(1.0f + e); return fmaxf(x, 0.f) + lg; }
; __device__ __forceinline__ void mixer_pre_item(int item, const float* const* in, int l, unsigned char* ws, LAS unsigned char* lds, int tid, int lane, int wave) {
;     ...
;         for (int t = 0; t < 16; ++t) { const float xc = bf2f(STGD[(t0 + t + 3) * 768 + cc]); float y = siluf_(w0 * xm3 + w1 * xm2 + w2 * xm1 + w3 * xc);
;             if (kind < 2) { const float ss = wave_sum(y * y); y *= qs * __builtin_amdgcn_rsqf(ss + EPS); }
;             dst[(size_t)t * 256] = f2bf(y);
;             xm3 = xm2; xm2 = xm1; xm1 = xc; }
;     }
;     if (tid < 128) { const int tok = tid >> 2, hh = tid & 3; const float* sd = (const float*)(ws + WS_R2 + R2_DNBA) + (g0 + tok) * 8;
;         const float beta = sigmoidf_(sd[hh]), g = -__expf(in[18][l * 4 + hh]) * softplusf_(sd[4 + hh] + in[19][l * 4 + hh]);
;         ((float*)(ws + WS_R2 + R2_GG))[(g0 + tok) * 4 + hh] = g; ((float*)(ws + WS_R2 + R2_BE))[(g0 + tok) * 4 + hh] = beta; }
.Lcv_nn2:
	v_cvt_pk_bf16_f32 v126, v128, v129
	s_nop 1
	v_mov_b32_dpp v127, v126 quad_perm:[1,0,3,2] row_mask:0xf bank_mask:0xf bound_ctrl:1
	v_perm_b32 v126, v127, v126, v132
	global_store_dword v[8:9], v126, off
	s_waitcnt lgkmcnt(0)
	v_lshlrev_b32_e32 v117, 16, v114
	v_lshlrev_b32_e32 v118, 16, v114
	v_lshlrev_b32_e32 v119, 16, v115
	v_mov_b32_e32 v116, v123
	v_pk_mul_f32 v[124:125], v[120:121], v[4:5] op_sel:[0,1]
	v_pk_mul_f32 v[126:127], v[122:123], v[4:5] op_sel_hi:[1,0]
	v_pk_mul_f32 v[130:131], v[116:117], v[6:7] op_sel_hi:[1,0]
	v_pk_add_f32 v[128:129], v[124:125], v[126:127]
	v_pk_mul_f32 v[124:125], v[118:119], v[6:7] op_sel:[0,1]
	v_pk_add_f32 v[128:129], v[130:131], v[128:129]
	v_pk_add_f32 v[128:129], v[128:129], v[124:125]
	v_pk_mul_f32 v[130:131], v[128:129], v[134:135] op_sel_hi:[1,0]
	v_exp_f32_e32 v130, v130
	v_exp_f32_e32 v131, v131
	s_nop 0
	v_pk_add_f32 v[130:131], v[130:131], v[136:137] op_sel_hi:[1,0]
	v_rcp_f32_e32 v130, v130
	v_rcp_f32_e32 v131, v131
	s_nop 0
	v_pk_mul_f32 v[128:129], v[128:129], v[130:131]
	s_and_b64 vcc, exec, s[38:39]
	s_cbranch_vccz .Lcv_nn3
	v_mul_f32_e32 v138, v128, v128
	v_mul_f32_e32 v139, v129, v129
	s_nop 0
	v_mov_b32_dpp v138, v138 quad_perm:[1,0,3,2] row_mask:0xf bank_mask:0xf bound_ctrl:1
	v_mov_b32_dpp v139, v139 quad_perm:[1,0,3,2] row_mask:0xf bank_mask:0xf bound_ctrl:1
	v_fmac_f32_e32 v138, v128, v128
	v_fmac_f32_e32 v139, v129, v129
	s_nop 0
	v_add_f32_dpp v138, v138, v138 quad_perm:[2,3,0,1] row_mask:0xf bank_mask:0xf bound_ctrl:1
	v_add_f32_dpp v139, v139, v139 quad_perm:[2,3,0,1] row_mask:0xf bank_mask:0xf bound_ctrl:1
	s_nop 0
	v_add_f32_dpp v138, v138, v138 row_half_mirror row_mask:0xf bank_mask:0xf bound_ctrl:1
	v_add_f32_dpp v139, v139, v139 row_half_mirror row_mask:0xf bank_mask:0xf bound_ctrl:1
	s_nop 0
	v_add_f32_dpp v138, v138, v138 row_mirror row_mask:0xf bank_mask:0xf bound_ctrl:1
	v_add_f32_dpp v139, v139, v139 row_mirror row_mask:0xf bank_mask:0xf bound_ctrl:1
	s_nop 0
	v_readlane_b32 s48, v138, 16
	v_readlane_b32 s49, v138, 48
	v_readlane_b32 s44, v138, 0
	v_readlane_b32 s45, v138, 32
	v_readlane_b32 s100, v139, 16
	v_readlane_b32 s101, v139, 48
	v_readlane_b32 s40, v139, 0
	v_readlane_b32 s41, v139, 32
	v_mov_b32_e32 v140, s48
	v_mov_b32_e32 v141, s49
	v_mov_b32_e32 v142, s100
	v_mov_b32_e32 v143, s101
	v_pk_add_f32 v[140:141], s[44:45], v[140:141]
	v_pk_add_f32 v[142:143], s[40:41], v[142:143]
	v_add_f32_e32 v138, v140, v141
	v_add_f32_e32 v139, v142, v143
	v_add_f32_e32 v138, 0x358637bd, v138
	v_add_f32_e32 v139, 0x358637bd, v139
	v_rsq_f32_e32 v138, v138
	v_rsq_f32_e32 v139, v139
	s_nop 0
	v_mul_f32_e32 v138, v0, v138
	v_mul_f32_e32 v139, v0, v139
	v_mul_f32_e32 v128, v128, v138
	v_mul_f32_e32 v129, v129, v139
.Lcv_nn3:
	v_cvt_pk_bf16_f32 v126, v128, v129
	s_nop 1
	v_mov_b32_dpp v127, v126 quad_perm:[1,0,3,2] row_mask:0xf bank_mask:0xf bound_ctrl:1
	v_perm_b32 v126, v127, v126, v132
	global_store_dword v[8:9], v126, off offset:1024
	s_addk_i32 s43, 0x3000
	v_lshl_add_u64 v[8:9], v[8:9], 0, s[4:5]
	s_cmpk_eq_i32 s43, 0x6000
	s_cbranch_scc0 .Lcv_loop
	s_branch .LBB0_614
.LBB0_633:
	v_cmp_gt_i32_e32 vcc, s76, v34
	s_and_saveexec_b64 s[38:39], vcc
	s_cbranch_execz .LBB0_639
	v_ashrrev_i32_e32 v2, 2, v34
	s_or_b32 s20, s20, s30
	v_ashrrev_i32_e32 v3, 31, v2
	v_lshl_add_u64 v[2:3], s[20:21], 0, v[2:3]
	v_readlane_b32 s20, v251, 10
	v_and_b32_e32 v4, 3, v34
	v_lshlrev_b64 v[6:7], 5, v[2:3]
	v_readlane_b32 s21, v251, 11
	v_lshlrev_b32_e32 v0, 2, v4
	v_readlane_b32 s48, v248, 55
	v_lshl_add_u64 v[6:7], s[20:21], 0, v[6:7]
	v_lshl_add_u64 v[6:7], v[6:7], 0, v[0:1]
	v_or_b32_e32 v0, s0, v4
	v_lshlrev_b64 v[8:9], 2, v[0:1]
	v_readlane_b32 s58, v250, 1
	v_readlane_b32 s59, v250, 2
	v_readlane_b32 s60, v250, 3
	v_readlane_b32 s61, v250, 4
	v_lshl_add_u64 v[10:11], s[58:59], 0, v[8:9]
	s_nop 0
	v_lshl_add_u64 v[6:7], s[60:61], 0, v[8:9]
	s_mov_b32 s20, 0xbfb8aa3b
	v_readlane_b32 s49, v248, 56
	v_readlane_b32 s50, v248, 57
	v_readlane_b32 s51, v248, 58
	v_readlane_b32 s52, v248, 59
	v_readlane_b32 s53, v248, 60
	v_readlane_b32 s54, v248, 61
	v_readlane_b32 s55, v248, 62
	v_readlane_b32 s56, v248, 63
	v_readlane_b32 s57, v250, 0
	v_readlane_b32 s62, v250, 5
	v_readlane_b32 s63, v250, 6
	s_waitcnt vmcnt(24)
	v_mov_b32_e32 v5, v172
	v_mov_b32_e32 v0, v173
	v_mov_b32_e32 v10, v174
	v_mov_b32_e32 v6, v175
	v_add_f32_e32 v6, v10, v6
	v_mul_f32_e64 v7, |v6|, s20
	v_exp_f32_e32 v8, v7
	s_mov_b32 s20, 0x3cf5c28f
	v_cmp_ngt_f32_e32 vcc, s20, v8
	s_and_saveexec_b64 s[20:21], vcc
	s_xor_b64 s[20:21], exec, s[20:21]
	s_cbranch_execz .LBB0_636
	v_add_f32_e32 v7, 1.0, v8
	s_mov_b32 s30, 0x800000
	v_cmp_gt_f32_e32 vcc, s30, v7
	s_mov_b32 s30, 0x3f317217
	s_nop 0
	v_cndmask_b32_e64 v8, 0, 32, vcc
	v_ldexp_f32 v7, v7, v8
	v_log_f32_e32 v7, v7
	s_nop 0
	v_mul_f32_e32 v8, 0x3f317217, v7
	v_fma_f32 v8, v7, s30, -v8
	v_fmac_f32_e32 v8, 0x3377d1cf, v7
	s_mov_b32 s30, 0x7f800000
	v_fmac_f32_e32 v8, 0x3f317217, v7
	v_cmp_lt_f32_e64 s[40:41], |v7|, s30
	s_nop 1
	v_cndmask_b32_e64 v7, v7, v8, s[40:41]
	v_cndmask_b32_e32 v8, 0, v232, vcc
	v_sub_f32_e32 v7, v7, v8
